# GU epilogue body rewritten by hand: packed f32 ops on accumulator pairs, rs folded into exp scale and rcp argument (4 packed + 4 trans per element pair), single running store address
# speedup vs baseline: 1.0148x; 1.0148x over previous
; __device__ __forceinline__ u32x2 pack4(const f32x4 v) { u32x2 w; w.x = cvt_pk_bf16(v[0], v[1]); w.y = cvt_pk_bf16(v[2], v[3]); return w; }
;     __device__ __forceinline__ void operator()(const f32x4 (&acc)[2][2][4][2], const Unit& u, int wr, int wc, int fr, int fq) const {
;     ...
;                 const int row = u.pm * BM + ai * HALF + wr * 64 + m * 16 + fr;
;                 const float rs = rsv[ai][m];
;                 u32x2 w[2];
; #pragma unroll
;                 for (int n = 0; n < 2; ++n) {
;                     const f32x4 g = acc[ai][0][m][n] * rs, up = acc[ai][1][m][n] * rs; f32x4 o;
; #pragma unroll
;                     for (int j = 0; j < 4; ++j) { const float e = __builtin_amdgcn_exp2f(-g[j] * kLog2e); o[j] = g[j] * up[j] * __builtin_amdgcn_rcpf(1.0f + e); }
;                     w[n] = pack4(o);
;                 }
;                 *(u32x4_*)(H + (size_t)row * 2816 + u.pn * 128 + wc * 32 + fq * 8) = (u32x4_){w[0].x, w[0].y, w[1].x, w[1].y};
.Lgu_rs_hit:
	s_and_b64 vcc, exec, s[38:39]
	v_mul_u32_u24_e32 v186, 0x1600, v162
	v_mov_b32_e32 v187, 0
	s_lshl_b32 s30, s72, 7
	s_ashr_i32 s31, s30, 31
	s_lshl_b64 s[30:31], s[30:31], 1
	v_lshl_add_u64 v[184:185], s[90:91], 0, v[186:187]
	v_lshl_add_u64 v[184:185], v[184:185], 0, s[30:31]
	v_lshl_add_u64 v[184:185], v[184:185], 0, s[18:19]
	v_lshl_add_u64 v[184:185], v[184:185], 0, v[208:209]
	s_mov_b32 s34, 0x16000
	s_mov_b32 s35, 0
	s_mov_b32 s30, 0x6e000
	s_mov_b32 s31, 0
	v_mul_f32_e32 v180, 0xbfb8aa3b, v164
	v_mul_f32_e32 v182, v164, v164
	v_rcp_f32_e32 v182, v182
	v_pk_mul_f32 v[168:169], v[120:121], v[180:181] op_sel_hi:[1,0]
	v_pk_mul_f32 v[170:171], v[122:123], v[180:181] op_sel_hi:[1,0]
	v_pk_mul_f32 v[172:173], v[116:117], v[180:181] op_sel_hi:[1,0]
	v_pk_mul_f32 v[174:175], v[118:119], v[180:181] op_sel_hi:[1,0]
	v_exp_f32_e32 v168, v168
	v_exp_f32_e32 v169, v169
	v_exp_f32_e32 v170, v170
	v_exp_f32_e32 v171, v171
	v_exp_f32_e32 v172, v172
	v_exp_f32_e32 v173, v173
	v_exp_f32_e32 v174, v174
	v_exp_f32_e32 v175, v175
	v_pk_mul_f32 v[120:121], v[120:121], v[124:125]
	v_pk_mul_f32 v[122:123], v[122:123], v[126:127]
	v_pk_mul_f32 v[116:117], v[116:117], v[112:113]
	v_pk_mul_f32 v[118:119], v[118:119], v[114:115]
	v_pk_fma_f32 v[168:169], v[168:169], v[182:183], v[182:183] op_sel_hi:[1,0,0]
	v_pk_fma_f32 v[170:171], v[170:171], v[182:183], v[182:183] op_sel_hi:[1,0,0]
	v_pk_fma_f32 v[172:173], v[172:173], v[182:183], v[182:183] op_sel_hi:[1,0,0]
	v_pk_fma_f32 v[174:175], v[174:175], v[182:183], v[182:183] op_sel_hi:[1,0,0]
	v_rcp_f32_e32 v168, v168
	v_rcp_f32_e32 v169, v169
	v_rcp_f32_e32 v170, v170
	v_rcp_f32_e32 v171, v171
	v_rcp_f32_e32 v172, v172
	v_rcp_f32_e32 v173, v173
	v_rcp_f32_e32 v174, v174
	v_rcp_f32_e32 v175, v175
	s_nop 0
	v_pk_mul_f32 v[120:121], v[120:121], v[168:169]
	v_pk_mul_f32 v[122:123], v[122:123], v[170:171]
	v_pk_mul_f32 v[116:117], v[116:117], v[172:173]
	v_pk_mul_f32 v[118:119], v[118:119], v[174:175]
	v_cvt_pk_bf16_f32 v176, v120, v121
	v_cvt_pk_bf16_f32 v177, v122, v123
	v_cvt_pk_bf16_f32 v178, v116, v117
	v_cvt_pk_bf16_f32 v179, v118, v119
	global_store_dwordx4 v[184:185], v[176:179], off
	v_lshl_add_u64 v[184:185], v[184:185], 0, s[34:35]
	v_mul_f32_e32 v180, 0xbfb8aa3b, v166
	v_mul_f32_e32 v182, v166, v166
	v_rcp_f32_e32 v182, v182
	v_pk_mul_f32 v[168:169], v[108:109], v[180:181] op_sel_hi:[1,0]
	v_pk_mul_f32 v[170:171], v[110:111], v[180:181] op_sel_hi:[1,0]
	v_pk_mul_f32 v[172:173], v[100:101], v[180:181] op_sel_hi:[1,0]
	v_pk_mul_f32 v[174:175], v[102:103], v[180:181] op_sel_hi:[1,0]
	v_exp_f32_e32 v168, v168
	v_exp_f32_e32 v169, v169
	v_exp_f32_e32 v170, v170
	v_exp_f32_e32 v171, v171
	v_exp_f32_e32 v172, v172
	v_exp_f32_e32 v173, v173
	v_exp_f32_e32 v174, v174
	v_exp_f32_e32 v175, v175
	v_pk_mul_f32 v[108:109], v[108:109], v[104:105]
	v_pk_mul_f32 v[110:111], v[110:111], v[106:107]
	v_pk_mul_f32 v[100:101], v[100:101], v[96:97]
	v_pk_mul_f32 v[102:103], v[102:103], v[98:99]
	v_pk_fma_f32 v[168:169], v[168:169], v[182:183], v[182:183] op_sel_hi:[1,0,0]
	v_pk_fma_f32 v[170:171], v[170:171], v[182:183], v[182:183] op_sel_hi:[1,0,0]
	v_pk_fma_f32 v[172:173], v[172:173], v[182:183], v[182:183] op_sel_hi:[1,0,0]
	v_pk_fma_f32 v[174:175], v[174:175], v[182:183], v[182:183] op_sel_hi:[1,0,0]
	v_rcp_f32_e32 v168, v168
	v_rcp_f32_e32 v169, v169
	v_rcp_f32_e32 v170, v170
	v_rcp_f32_e32 v171, v171
	v_rcp_f32_e32 v172, v172
	v_rcp_f32_e32 v173, v173
	v_rcp_f32_e32 v174, v174
	v_rcp_f32_e32 v175, v175
	s_nop 0
	v_pk_mul_f32 v[108:109], v[108:109], v[168:169]
	v_pk_mul_f32 v[110:111], v[110:111], v[170:171]
	v_pk_mul_f32 v[100:101], v[100:101], v[172:173]
	v_pk_mul_f32 v[102:103], v[102:103], v[174:175]
	v_cvt_pk_bf16_f32 v176, v108, v109
	v_cvt_pk_bf16_f32 v177, v110, v111
	v_cvt_pk_bf16_f32 v178, v100, v101
	v_cvt_pk_bf16_f32 v179, v102, v103
	global_store_dwordx4 v[184:185], v[176:179], off
	v_lshl_add_u64 v[184:185], v[184:185], 0, s[34:35]
	v_mul_f32_e32 v180, 0xbfb8aa3b, v160
	v_mul_f32_e32 v182, v160, v160
	v_rcp_f32_e32 v182, v182
	v_pk_mul_f32 v[168:169], v[92:93], v[180:181] op_sel_hi:[1,0]
	v_pk_mul_f32 v[170:171], v[94:95], v[180:181] op_sel_hi:[1,0]
	v_pk_mul_f32 v[172:173], v[84:85], v[180:181] op_sel_hi:[1,0]
	v_pk_mul_f32 v[174:175], v[86:87], v[180:181] op_sel_hi:[1,0]
	v_exp_f32_e32 v168, v168
	v_exp_f32_e32 v169, v169
	v_exp_f32_e32 v170, v170
	v_exp_f32_e32 v171, v171
	v_exp_f32_e32 v172, v172
	v_exp_f32_e32 v173, v173
	v_exp_f32_e32 v174, v174
	v_exp_f32_e32 v175, v175
	v_pk_mul_f32 v[92:93], v[92:93], v[88:89]
	v_pk_mul_f32 v[94:95], v[94:95], v[90:91]
	v_pk_mul_f32 v[84:85], v[84:85], v[80:81]
	v_pk_mul_f32 v[86:87], v[86:87], v[82:83]
	v_pk_fma_f32 v[168:169], v[168:169], v[182:183], v[182:183] op_sel_hi:[1,0,0]
	v_pk_fma_f32 v[170:171], v[170:171], v[182:183], v[182:183] op_sel_hi:[1,0,0]
	v_pk_fma_f32 v[172:173], v[172:173], v[182:183], v[182:183] op_sel_hi:[1,0,0]
	v_pk_fma_f32 v[174:175], v[174:175], v[182:183], v[182:183] op_sel_hi:[1,0,0]
	v_rcp_f32_e32 v168, v168
	v_rcp_f32_e32 v169, v169
	v_rcp_f32_e32 v170, v170
	v_rcp_f32_e32 v171, v171
	v_rcp_f32_e32 v172, v172
	v_rcp_f32_e32 v173, v173
	v_rcp_f32_e32 v174, v174
	v_rcp_f32_e32 v175, v175
	s_nop 0
	v_pk_mul_f32 v[92:93], v[92:93], v[168:169]
	v_pk_mul_f32 v[94:95], v[94:95], v[170:171]
	v_pk_mul_f32 v[84:85], v[84:85], v[172:173]
	v_pk_mul_f32 v[86:87], v[86:87], v[174:175]
	v_cvt_pk_bf16_f32 v176, v92, v93
	v_cvt_pk_bf16_f32 v177, v94, v95
	v_cvt_pk_bf16_f32 v178, v84, v85
	v_cvt_pk_bf16_f32 v179, v86, v87
	global_store_dwordx4 v[184:185], v[176:179], off
	v_lshl_add_u64 v[184:185], v[184:185], 0, s[34:35]
; __device__ __forceinline__ u32x2 pack4(const f32x4 v) { u32x2 w; w.x = cvt_pk_bf16(v[0], v[1]); w.y = cvt_pk_bf16(v[2], v[3]); return w; }
;     __device__ __forceinline__ void operator()(const f32x4 (&acc)[2][2][4][2], const Unit& u, int wr, int wc, int fr, int fq) const {
;     ...
;                 const int row = u.pm * BM + ai * HALF + wr * 64 + m * 16 + fr;
;                 const float rs = rsv[ai][m];
;                 u32x2 w[2];
; #pragma unroll
;                 for (int n = 0; n < 2; ++n) {
;                     const f32x4 g = acc[ai][0][m][n] * rs, up = acc[ai][1][m][n] * rs; f32x4 o;
; #pragma unroll
;                     for (int j = 0; j < 4; ++j) { const float e = __builtin_amdgcn_exp2f(-g[j] * kLog2e); o[j] = g[j] * up[j] * __builtin_amdgcn_rcpf(1.0f + e); }
;                     w[n] = pack4(o);
;                 }
;                 *(u32x4_*)(H + (size_t)row * 2816 + u.pn * 128 + wc * 32 + fq * 8) = (u32x4_){w[0].x, w[0].y, w[1].x, w[1].y};
	v_mul_f32_e32 v180, 0xbfb8aa3b, v158
	v_mul_f32_e32 v182, v158, v158
	v_rcp_f32_e32 v182, v182
	v_pk_mul_f32 v[168:169], v[76:77], v[180:181] op_sel_hi:[1,0]
	v_pk_mul_f32 v[170:171], v[78:79], v[180:181] op_sel_hi:[1,0]
	v_pk_mul_f32 v[172:173], v[68:69], v[180:181] op_sel_hi:[1,0]
	v_pk_mul_f32 v[174:175], v[70:71], v[180:181] op_sel_hi:[1,0]
	v_exp_f32_e32 v168, v168
	v_exp_f32_e32 v169, v169
	v_exp_f32_e32 v170, v170
	v_exp_f32_e32 v171, v171
	v_exp_f32_e32 v172, v172
	v_exp_f32_e32 v173, v173
	v_exp_f32_e32 v174, v174
	v_exp_f32_e32 v175, v175
	v_pk_mul_f32 v[76:77], v[76:77], v[72:73]
	v_pk_mul_f32 v[78:79], v[78:79], v[74:75]
	v_pk_mul_f32 v[68:69], v[68:69], v[64:65]
	v_pk_mul_f32 v[70:71], v[70:71], v[66:67]
	v_pk_fma_f32 v[168:169], v[168:169], v[182:183], v[182:183] op_sel_hi:[1,0,0]
	v_pk_fma_f32 v[170:171], v[170:171], v[182:183], v[182:183] op_sel_hi:[1,0,0]
	v_pk_fma_f32 v[172:173], v[172:173], v[182:183], v[182:183] op_sel_hi:[1,0,0]
	v_pk_fma_f32 v[174:175], v[174:175], v[182:183], v[182:183] op_sel_hi:[1,0,0]
	v_rcp_f32_e32 v168, v168
	v_rcp_f32_e32 v169, v169
	v_rcp_f32_e32 v170, v170
	v_rcp_f32_e32 v171, v171
	v_rcp_f32_e32 v172, v172
	v_rcp_f32_e32 v173, v173
	v_rcp_f32_e32 v174, v174
	v_rcp_f32_e32 v175, v175
	s_nop 0
	v_pk_mul_f32 v[76:77], v[76:77], v[168:169]
	v_pk_mul_f32 v[78:79], v[78:79], v[170:171]
	v_pk_mul_f32 v[68:69], v[68:69], v[172:173]
	v_pk_mul_f32 v[70:71], v[70:71], v[174:175]
	v_cvt_pk_bf16_f32 v176, v76, v77
	v_cvt_pk_bf16_f32 v177, v78, v79
	v_cvt_pk_bf16_f32 v178, v68, v69
	v_cvt_pk_bf16_f32 v179, v70, v71
	global_store_dwordx4 v[184:185], v[176:179], off
	v_lshl_add_u64 v[184:185], v[184:185], 0, s[30:31]
	v_mul_f32_e32 v180, 0xbfb8aa3b, v156
	v_mul_f32_e32 v182, v156, v156
	v_rcp_f32_e32 v182, v182
	v_pk_mul_f32 v[168:169], v[60:61], v[180:181] op_sel_hi:[1,0]
	v_pk_mul_f32 v[170:171], v[62:63], v[180:181] op_sel_hi:[1,0]
	v_pk_mul_f32 v[172:173], v[52:53], v[180:181] op_sel_hi:[1,0]
	v_pk_mul_f32 v[174:175], v[54:55], v[180:181] op_sel_hi:[1,0]
	v_exp_f32_e32 v168, v168
	v_exp_f32_e32 v169, v169
	v_exp_f32_e32 v170, v170
	v_exp_f32_e32 v171, v171
	v_exp_f32_e32 v172, v172
	v_exp_f32_e32 v173, v173
	v_exp_f32_e32 v174, v174
	v_exp_f32_e32 v175, v175
	v_pk_mul_f32 v[60:61], v[60:61], v[56:57]
	v_pk_mul_f32 v[62:63], v[62:63], v[58:59]
	v_pk_mul_f32 v[52:53], v[52:53], v[48:49]
	v_pk_mul_f32 v[54:55], v[54:55], v[50:51]
	v_pk_fma_f32 v[168:169], v[168:169], v[182:183], v[182:183] op_sel_hi:[1,0,0]
	v_pk_fma_f32 v[170:171], v[170:171], v[182:183], v[182:183] op_sel_hi:[1,0,0]
	v_pk_fma_f32 v[172:173], v[172:173], v[182:183], v[182:183] op_sel_hi:[1,0,0]
	v_pk_fma_f32 v[174:175], v[174:175], v[182:183], v[182:183] op_sel_hi:[1,0,0]
	v_rcp_f32_e32 v168, v168
	v_rcp_f32_e32 v169, v169
	v_rcp_f32_e32 v170, v170
	v_rcp_f32_e32 v171, v171
	v_rcp_f32_e32 v172, v172
	v_rcp_f32_e32 v173, v173
	v_rcp_f32_e32 v174, v174
	v_rcp_f32_e32 v175, v175
	s_nop 0
	v_pk_mul_f32 v[60:61], v[60:61], v[168:169]
	v_pk_mul_f32 v[62:63], v[62:63], v[170:171]
	v_pk_mul_f32 v[52:53], v[52:53], v[172:173]
	v_pk_mul_f32 v[54:55], v[54:55], v[174:175]
	v_cvt_pk_bf16_f32 v176, v60, v61
	v_cvt_pk_bf16_f32 v177, v62, v63
	v_cvt_pk_bf16_f32 v178, v52, v53
	v_cvt_pk_bf16_f32 v179, v54, v55
	global_store_dwordx4 v[184:185], v[176:179], off
	v_lshl_add_u64 v[184:185], v[184:185], 0, s[34:35]
	v_mul_f32_e32 v180, 0xbfb8aa3b, v154
	v_mul_f32_e32 v182, v154, v154
	v_rcp_f32_e32 v182, v182
	v_pk_mul_f32 v[168:169], v[44:45], v[180:181] op_sel_hi:[1,0]
	v_pk_mul_f32 v[170:171], v[46:47], v[180:181] op_sel_hi:[1,0]
	v_pk_mul_f32 v[172:173], v[36:37], v[180:181] op_sel_hi:[1,0]
	v_pk_mul_f32 v[174:175], v[38:39], v[180:181] op_sel_hi:[1,0]
	v_exp_f32_e32 v168, v168
	v_exp_f32_e32 v169, v169
	v_exp_f32_e32 v170, v170
	v_exp_f32_e32 v171, v171
	v_exp_f32_e32 v172, v172
	v_exp_f32_e32 v173, v173
	v_exp_f32_e32 v174, v174
	v_exp_f32_e32 v175, v175
	v_pk_mul_f32 v[44:45], v[44:45], v[40:41]
	v_pk_mul_f32 v[46:47], v[46:47], v[42:43]
	v_pk_mul_f32 v[36:37], v[36:37], v[32:33]
	v_pk_mul_f32 v[38:39], v[38:39], v[34:35]
	v_pk_fma_f32 v[168:169], v[168:169], v[182:183], v[182:183] op_sel_hi:[1,0,0]
	v_pk_fma_f32 v[170:171], v[170:171], v[182:183], v[182:183] op_sel_hi:[1,0,0]
; __device__ __forceinline__ u32x2 pack4(const f32x4 v) { u32x2 w; w.x = cvt_pk_bf16(v[0], v[1]); w.y = cvt_pk_bf16(v[2], v[3]); return w; }
; #define PG8_BAR __builtin_amdgcn_s_barrier()
;     __device__ __forceinline__ void operator()(const f32x4 (&acc)[2][2][4][2], const Unit& u, int wr, int wc, int fr, int fq) const {
;     ...
;                 const int row = u.pm * BM + ai * HALF + wr * 64 + m * 16 + fr;
;                 const float rs = rsv[ai][m];
;                 u32x2 w[2];
; #pragma unroll
;                 for (int n = 0; n < 2; ++n) {
;                     const f32x4 g = acc[ai][0][m][n] * rs, up = acc[ai][1][m][n] * rs; f32x4 o;
; #pragma unroll
;                     for (int j = 0; j < 4; ++j) { const float e = __builtin_amdgcn_exp2f(-g[j] * kLog2e); o[j] = g[j] * up[j] * __builtin_amdgcn_rcpf(1.0f + e); }
;                     w[n] = pack4(o);
;                 }
;                 *(u32x4_*)(H + (size_t)row * 2816 + u.pn * 128 + wc * 32 + fq * 8) = (u32x4_){w[0].x, w[0].y, w[1].x, w[1].y};
; template <class Epi, class Sched, bool ALIGN_EPI = false, bool SP2 = false>
; __device__ __forceinline__ void gemm_phase(PG8_LAS unsigned char* lds, const Gemm g, const Sched& S, const Epi& E) {
;     ...
;         if (!has_next) break;
; #pragma unroll
;         for (int a = 0; a < 2; ++a)
; #pragma unroll
;             for (int b = 0; b < 2; ++b)
; #pragma unroll
;                 for (int m = 0; m < 4; ++m)
; #pragma unroll
;                     for (int n = 0; n < 2; ++n) acc[a][b][m][n] = (f32x4){0.f, 0.f, 0.f, 0.f};
;         cur = nxt; cA = nA; cB = nB; ++ui;
;         if constexpr (ALIGN_EPI) { if (wr == 1) PG8_BAR; }
	v_pk_fma_f32 v[172:173], v[172:173], v[182:183], v[182:183] op_sel_hi:[1,0,0]
	v_pk_fma_f32 v[174:175], v[174:175], v[182:183], v[182:183] op_sel_hi:[1,0,0]
	v_rcp_f32_e32 v168, v168
	v_rcp_f32_e32 v169, v169
	v_rcp_f32_e32 v170, v170
	v_rcp_f32_e32 v171, v171
	v_rcp_f32_e32 v172, v172
	v_rcp_f32_e32 v173, v173
	v_rcp_f32_e32 v174, v174
	v_rcp_f32_e32 v175, v175
	s_nop 0
	v_pk_mul_f32 v[44:45], v[44:45], v[168:169]
	v_pk_mul_f32 v[46:47], v[46:47], v[170:171]
	v_pk_mul_f32 v[36:37], v[36:37], v[172:173]
	v_pk_mul_f32 v[38:39], v[38:39], v[174:175]
	v_cvt_pk_bf16_f32 v176, v44, v45
	v_cvt_pk_bf16_f32 v177, v46, v47
	v_cvt_pk_bf16_f32 v178, v36, v37
	v_cvt_pk_bf16_f32 v179, v38, v39
	global_store_dwordx4 v[184:185], v[176:179], off
	v_lshl_add_u64 v[184:185], v[184:185], 0, s[34:35]
	v_mul_f32_e32 v180, 0xbfb8aa3b, v150
	v_mul_f32_e32 v182, v150, v150
	v_rcp_f32_e32 v182, v182
	v_pk_mul_f32 v[168:169], v[28:29], v[180:181] op_sel_hi:[1,0]
	v_pk_mul_f32 v[170:171], v[30:31], v[180:181] op_sel_hi:[1,0]
	v_pk_mul_f32 v[172:173], v[20:21], v[180:181] op_sel_hi:[1,0]
	v_pk_mul_f32 v[174:175], v[22:23], v[180:181] op_sel_hi:[1,0]
	v_exp_f32_e32 v168, v168
	v_exp_f32_e32 v169, v169
	v_exp_f32_e32 v170, v170
	v_exp_f32_e32 v171, v171
	v_exp_f32_e32 v172, v172
	v_exp_f32_e32 v173, v173
	v_exp_f32_e32 v174, v174
	v_exp_f32_e32 v175, v175
	v_pk_mul_f32 v[28:29], v[28:29], v[24:25]
	v_pk_mul_f32 v[30:31], v[30:31], v[26:27]
	v_pk_mul_f32 v[20:21], v[20:21], v[16:17]
	v_pk_mul_f32 v[22:23], v[22:23], v[18:19]
	v_pk_fma_f32 v[168:169], v[168:169], v[182:183], v[182:183] op_sel_hi:[1,0,0]
	v_pk_fma_f32 v[170:171], v[170:171], v[182:183], v[182:183] op_sel_hi:[1,0,0]
	v_pk_fma_f32 v[172:173], v[172:173], v[182:183], v[182:183] op_sel_hi:[1,0,0]
	v_pk_fma_f32 v[174:175], v[174:175], v[182:183], v[182:183] op_sel_hi:[1,0,0]
	v_rcp_f32_e32 v168, v168
	v_rcp_f32_e32 v169, v169
	v_rcp_f32_e32 v170, v170
	v_rcp_f32_e32 v171, v171
	v_rcp_f32_e32 v172, v172
	v_rcp_f32_e32 v173, v173
	v_rcp_f32_e32 v174, v174
	v_rcp_f32_e32 v175, v175
	s_nop 0
	v_pk_mul_f32 v[28:29], v[28:29], v[168:169]
	v_pk_mul_f32 v[30:31], v[30:31], v[170:171]
	v_pk_mul_f32 v[20:21], v[20:21], v[172:173]
	v_pk_mul_f32 v[22:23], v[22:23], v[174:175]
	v_cvt_pk_bf16_f32 v176, v28, v29
	v_cvt_pk_bf16_f32 v177, v30, v31
	v_cvt_pk_bf16_f32 v178, v20, v21
	v_cvt_pk_bf16_f32 v179, v22, v23
	global_store_dwordx4 v[184:185], v[176:179], off
	v_lshl_add_u64 v[184:185], v[184:185], 0, s[34:35]
	v_mul_f32_e32 v180, 0xbfb8aa3b, v146
	v_mul_f32_e32 v182, v146, v146
	v_rcp_f32_e32 v182, v182
	v_pk_mul_f32 v[168:169], v[12:13], v[180:181] op_sel_hi:[1,0]
	v_pk_mul_f32 v[170:171], v[14:15], v[180:181] op_sel_hi:[1,0]
	v_pk_mul_f32 v[172:173], v[4:5], v[180:181] op_sel_hi:[1,0]
	v_pk_mul_f32 v[174:175], v[6:7], v[180:181] op_sel_hi:[1,0]
	v_exp_f32_e32 v168, v168
	v_exp_f32_e32 v169, v169
	v_exp_f32_e32 v170, v170
	v_exp_f32_e32 v171, v171
	v_exp_f32_e32 v172, v172
	v_exp_f32_e32 v173, v173
	v_exp_f32_e32 v174, v174
	v_exp_f32_e32 v175, v175
	v_pk_mul_f32 v[12:13], v[12:13], v[8:9]
	v_pk_mul_f32 v[14:15], v[14:15], v[10:11]
	v_pk_mul_f32 v[4:5], v[4:5], v[0:1]
	v_pk_mul_f32 v[6:7], v[6:7], v[2:3]
	v_pk_fma_f32 v[168:169], v[168:169], v[182:183], v[182:183] op_sel_hi:[1,0,0]
	v_pk_fma_f32 v[170:171], v[170:171], v[182:183], v[182:183] op_sel_hi:[1,0,0]
	v_pk_fma_f32 v[172:173], v[172:173], v[182:183], v[182:183] op_sel_hi:[1,0,0]
	v_pk_fma_f32 v[174:175], v[174:175], v[182:183], v[182:183] op_sel_hi:[1,0,0]
	v_rcp_f32_e32 v168, v168
	v_rcp_f32_e32 v169, v169
	v_rcp_f32_e32 v170, v170
	v_rcp_f32_e32 v171, v171
	v_rcp_f32_e32 v172, v172
	v_rcp_f32_e32 v173, v173
	v_rcp_f32_e32 v174, v174
	v_rcp_f32_e32 v175, v175
	s_nop 0
	v_pk_mul_f32 v[12:13], v[12:13], v[168:169]
	v_pk_mul_f32 v[14:15], v[14:15], v[170:171]
	v_pk_mul_f32 v[4:5], v[4:5], v[172:173]
	v_pk_mul_f32 v[6:7], v[6:7], v[174:175]
	v_cvt_pk_bf16_f32 v176, v12, v13
	v_cvt_pk_bf16_f32 v177, v14, v15
	v_cvt_pk_bf16_f32 v178, v4, v5
	v_cvt_pk_bf16_f32 v179, v6, v7
	global_store_dwordx4 v[184:185], v[176:179], off
	s_mov_b64 s[30:31], -1
	s_cbranch_vccnz .LBB0_182
	s_andn2_b64 vcc, exec, s[28:29]
	s_cbranch_vccnz .LBB0_181
	s_barrier
	s_branch .LBB0_181
